# layer-0 non-WIN weight transposes hidden in mixers(L0) phase on blocks>=160, WUP(L1) in mixers(L1); slot8 takes WIN/WA/WB/WOUT of L1; phase 1 transposes WIN(L0) only
# speedup vs baseline: 1.0236x; 1.0106x over previous
.LBB0_231:
	s_or_b64 exec, exec, s[0:1]
	s_cmp_lt_u32 s96, 128
	s_cbranch_scc1 .Ltrp1_A_skip
	s_load_dwordx2 s[0:1], s[92:93], 0x58
	s_load_dwordx2 s[2:3], s[92:93], 0xb8
	s_load_dwordx2 s[4:5], s[92:93], 0xc0
	s_load_dwordx2 s[6:7], s[92:93], 0xc8
	s_load_dwordx2 s[8:9], s[92:93], 0xd0
	s_load_dwordx2 s[10:11], s[92:93], 0xe8
	v_and_b32_e32 v74, 63, v154
	v_lshrrev_b32_e32 v75, 6, v154
	v_mul_u32_u24_e32 v75, 0x2100, v75
	v_lshrrev_b32_e32 v3, 5, v74
	v_and_b32_e32 v4, 31, v74
	v_lshlrev_b32_e32 v4, 2, v4
	v_lshrrev_b32_e32 v5, 3, v74
	v_and_b32_e32 v6, 7, v74
	v_mul_u32_u24_e32 v2, 264, v6
	v_add_u32_e32 v2, v2, v5
	v_lshl_add_u32 v2, v2, 2, v75
	v_lshlrev_b32_e32 v6, 4, v6
	v_mul_u32_u24_e32 v1, 132, v5
	v_add3_u32 v1, v1, v6, v75
	v_readfirstlane_b32 s13, v154
	s_lshr_b32 s13, s13, 6
	s_lshl_b32 s26, s96, 3
	s_add_u32 s13, s13, s26
	s_mov_b32 s12, s13
	s_waitcnt lgkmcnt(0)
	s_cmp_ge_u32 s12, 12288
	s_cbranch_scc1 .Ltrb_done
	s_cmp_ge_u32 s12, 33280
	s_cselect_b32 s41, 1, 0
	s_cselect_b32 s26, 33280, 0
	s_sub_u32 s42, s12, s26
	s_cmp_ge_u32 s42, 12288
	s_cbranch_scc1 .Ltrb_m2
	s_mul_i32 s43, s42, 43691
	s_lshr_b32 s43, s43, 24
	s_mul_i32 s26, s43, 384
	s_sub_u32 s44, s42, s26
	s_mov_b32 s14, s0
	s_mov_b32 s15, s1
	s_mov_b32 s36, 0xc000
	s_mov_b32 s37, 0x6000000
	s_mov_b32 s38, 0x0
	s_mov_b32 s39, 0x3000000
	s_mov_b32 s40, 0x1000
	s_branch .Ltrb_dec_done1

.Ltrb_loop:
	s_add_u32 s12, s12, 2048
	s_cmp_lt_u32 s12, 12288
	s_cselect_b32 s24, 1, 0
	s_cbranch_scc0 .Ltrb_nonext8
	s_cmp_ge_u32 s12, 33280
	s_cselect_b32 s41, 1, 0
	s_cselect_b32 s26, 33280, 0
	s_sub_u32 s42, s12, s26
	s_cmp_ge_u32 s42, 12288
	s_cbranch_scc1 .Ltrb_m11
	s_mul_i32 s43, s42, 43691
	s_lshr_b32 s43, s43, 24
	s_mul_i32 s26, s43, 384
	s_sub_u32 s44, s42, s26
	s_mov_b32 s16, s0
	s_mov_b32 s17, s1
	s_mov_b32 s36, 0xc000
	s_mov_b32 s37, 0x6000000
	s_mov_b32 s38, 0x0
	s_mov_b32 s39, 0x3000000
	s_mov_b32 s40, 0x1000
	s_branch .Ltrb_dec_done10

.Ltrb_after9:
	ds_write_b32 v1, v10 offset:0
	ds_write_b32 v1, v11 offset:4
	ds_write_b32 v1, v12 offset:8
	ds_write_b32 v1, v13 offset:12
	ds_write_b32 v1, v14 offset:1056
	ds_write_b32 v1, v15 offset:1060
	ds_write_b32 v1, v16 offset:1064
	ds_write_b32 v1, v17 offset:1068
	ds_write_b32 v1, v18 offset:2112
	ds_write_b32 v1, v19 offset:2116
	ds_write_b32 v1, v20 offset:2120
	ds_write_b32 v1, v21 offset:2124
	ds_write_b32 v1, v22 offset:3168
	ds_write_b32 v1, v23 offset:3172
	ds_write_b32 v1, v24 offset:3176
	ds_write_b32 v1, v25 offset:3180
	ds_write_b32 v1, v26 offset:4224
	ds_write_b32 v1, v27 offset:4228
	ds_write_b32 v1, v28 offset:4232
	ds_write_b32 v1, v29 offset:4236
	ds_write_b32 v1, v30 offset:5280
	ds_write_b32 v1, v31 offset:5284
	ds_write_b32 v1, v32 offset:5288
	ds_write_b32 v1, v33 offset:5292
	ds_write_b32 v1, v34 offset:6336
	ds_write_b32 v1, v35 offset:6340
	ds_write_b32 v1, v36 offset:6344
	ds_write_b32 v1, v37 offset:6348
	ds_write_b32 v1, v38 offset:7392
	ds_write_b32 v1, v39 offset:7396
	ds_write_b32 v1, v40 offset:7400
	ds_write_b32 v1, v41 offset:7404
	v_mad_u32_u24 v9, v5, s22, v6
	s_lshl_b32 s46, s22, 3
	s_waitcnt lgkmcnt(0)
	ds_read_b32 v74, v2 offset:0
	ds_read_b32 v75, v2 offset:132
	ds_read_b32 v76, v2 offset:264
	ds_read_b32 v77, v2 offset:396
	ds_read_b32 v78, v2 offset:528
	ds_read_b32 v79, v2 offset:660
	ds_read_b32 v80, v2 offset:792
	ds_read_b32 v81, v2 offset:924
	ds_read_b32 v82, v2 offset:32
	ds_read_b32 v83, v2 offset:164
	ds_read_b32 v84, v2 offset:296
	ds_read_b32 v85, v2 offset:428
	ds_read_b32 v86, v2 offset:560
	ds_read_b32 v87, v2 offset:692
	ds_read_b32 v88, v2 offset:824
	ds_read_b32 v89, v2 offset:956
	s_waitcnt lgkmcnt(8)
	v_cvt_pk_bf16_f32 v106, v74, v75
	v_cvt_pk_bf16_f32 v107, v76, v77
	v_cvt_pk_bf16_f32 v108, v78, v79
	v_cvt_pk_bf16_f32 v109, v80, v81
	global_store_dwordx4 v9, v[106:109], s[18:19]
	s_add_u32 s18, s18, s46
	s_addc_u32 s19, s19, 0
	ds_read_b32 v90, v2 offset:64
	ds_read_b32 v91, v2 offset:196
	ds_read_b32 v92, v2 offset:328
	ds_read_b32 v93, v2 offset:460
	ds_read_b32 v94, v2 offset:592
	ds_read_b32 v95, v2 offset:724
	ds_read_b32 v96, v2 offset:856
	ds_read_b32 v97, v2 offset:988
	s_waitcnt lgkmcnt(8)
	v_cvt_pk_bf16_f32 v110, v82, v83
	v_cvt_pk_bf16_f32 v111, v84, v85
	v_cvt_pk_bf16_f32 v112, v86, v87
	v_cvt_pk_bf16_f32 v113, v88, v89
	global_store_dwordx4 v9, v[110:113], s[18:19]
	s_add_u32 s18, s18, s46
	s_addc_u32 s19, s19, 0
	ds_read_b32 v98, v2 offset:96
	ds_read_b32 v99, v2 offset:228
	ds_read_b32 v100, v2 offset:360
	ds_read_b32 v101, v2 offset:492
	ds_read_b32 v102, v2 offset:624
	ds_read_b32 v103, v2 offset:756
	ds_read_b32 v104, v2 offset:888
	ds_read_b32 v105, v2 offset:1020
	s_waitcnt lgkmcnt(8)
	v_cvt_pk_bf16_f32 v106, v90, v91
	v_cvt_pk_bf16_f32 v107, v92, v93
	v_cvt_pk_bf16_f32 v108, v94, v95
	v_cvt_pk_bf16_f32 v109, v96, v97
	global_store_dwordx4 v9, v[106:109], s[18:19]
	s_add_u32 s18, s18, s46
	s_addc_u32 s19, s19, 0
	s_waitcnt lgkmcnt(0)
	v_cvt_pk_bf16_f32 v110, v98, v99
	v_cvt_pk_bf16_f32 v111, v100, v101
	v_cvt_pk_bf16_f32 v112, v102, v103
	v_cvt_pk_bf16_f32 v113, v104, v105
	global_store_dwordx4 v9, v[110:113], s[18:19]
	s_cmp_eq_u32 s24, 0
	s_cbranch_scc1 .Ltrb_done
	s_add_u32 s12, s12, 2048
	s_cmp_lt_u32 s12, 12288
	s_cselect_b32 s24, 1, 0
	s_cbranch_scc0 .Ltrb_nonext17
	s_cmp_ge_u32 s12, 33280
	s_cselect_b32 s41, 1, 0
	s_cselect_b32 s26, 33280, 0
	s_sub_u32 s42, s12, s26
	s_cmp_ge_u32 s42, 12288
	s_cbranch_scc1 .Ltrb_m20
	s_mul_i32 s43, s42, 43691
	s_lshr_b32 s43, s43, 24
	s_mul_i32 s26, s43, 384
	s_sub_u32 s44, s42, s26
	s_mov_b32 s14, s0
	s_mov_b32 s15, s1
	s_mov_b32 s36, 0xc000
	s_mov_b32 s37, 0x6000000
	s_mov_b32 s38, 0x0
	s_mov_b32 s39, 0x3000000
	s_mov_b32 s40, 0x1000
	s_branch .Ltrb_dec_done19

.Ltrp1_B:
	s_cmp_ge_u32 s96, 128
	s_cbranch_scc1 .LBB0_257
	s_load_dwordx2 s[0:1], s[92:93], 0x58
	s_load_dwordx2 s[2:3], s[92:93], 0xb8
	s_load_dwordx2 s[4:5], s[92:93], 0xc0
	s_load_dwordx2 s[6:7], s[92:93], 0xc8
	s_load_dwordx2 s[8:9], s[92:93], 0xd0
	s_load_dwordx2 s[10:11], s[92:93], 0xe8
	v_and_b32_e32 v74, 63, v154
	v_lshrrev_b32_e32 v75, 6, v154
	v_mul_u32_u24_e32 v75, 0x2100, v75
	v_lshrrev_b32_e32 v3, 5, v74
	v_and_b32_e32 v4, 31, v74
	v_lshlrev_b32_e32 v4, 2, v4
	v_lshrrev_b32_e32 v5, 3, v74
	v_and_b32_e32 v6, 7, v74
	v_mul_u32_u24_e32 v2, 264, v6
	v_add_u32_e32 v2, v2, v5
	v_lshl_add_u32 v2, v2, 2, v75
	v_lshlrev_b32_e32 v6, 4, v6
	v_mul_u32_u24_e32 v1, 132, v5
	v_add3_u32 v1, v1, v6, v75
	v_readfirstlane_b32 s13, v154
	s_lshr_b32 s13, s13, 6
	s_lshl_b32 s26, s96, 3
	s_add_u32 s13, s13, s26
	s_mov_b32 s12, s13
	s_waitcnt lgkmcnt(0)
	s_cmp_ge_u32 s12, 12288
	s_cbranch_scc1 .Ltrc_done
	s_cmp_ge_u32 s12, 33280
	s_cselect_b32 s41, 1, 0
	s_cselect_b32 s26, 33280, 0
	s_sub_u32 s42, s12, s26
	s_cmp_ge_u32 s42, 12288
	s_cbranch_scc1 .Ltrc_m2
	s_mul_i32 s43, s42, 43691
	s_lshr_b32 s43, s43, 24
	s_mul_i32 s26, s43, 384
	s_sub_u32 s44, s42, s26
	s_mov_b32 s14, s0
	s_mov_b32 s15, s1
	s_mov_b32 s36, 0xc000
	s_mov_b32 s37, 0x6000000
	s_mov_b32 s38, 0x0
	s_mov_b32 s39, 0x3000000
	s_mov_b32 s40, 0x1000
	s_branch .Ltrc_dec_done1

.LBB0_493:
	s_cmp_lt_u32 s96, 160
	s_cbranch_scc1 .Lmix0_skip
	s_load_dwordx2 s[0:1], s[92:93], 0x58
	s_load_dwordx2 s[2:3], s[92:93], 0xb8
	s_load_dwordx2 s[4:5], s[92:93], 0xc0
	s_load_dwordx2 s[6:7], s[92:93], 0xc8
	s_load_dwordx2 s[8:9], s[92:93], 0xd0
	s_load_dwordx2 s[10:11], s[92:93], 0xe8
	v_and_b32_e32 v74, 63, v154
	v_lshrrev_b32_e32 v75, 6, v154
	v_mul_u32_u24_e32 v75, 0x2100, v75
	v_lshrrev_b32_e32 v3, 5, v74
	v_and_b32_e32 v4, 31, v74
	v_lshlrev_b32_e32 v4, 2, v4
	v_lshrrev_b32_e32 v5, 3, v74
	v_and_b32_e32 v6, 7, v74
	v_mul_u32_u24_e32 v2, 264, v6
	v_add_u32_e32 v2, v2, v5
	v_lshl_add_u32 v2, v2, 2, v75
	v_lshlrev_b32_e32 v6, 4, v6
	v_mul_u32_u24_e32 v1, 132, v5
	v_add3_u32 v1, v1, v6, v75
	v_readfirstlane_b32 s13, v154
	s_lshr_b32 s13, s13, 6
	s_lshl_b32 s26, s96, 3
	s_add_u32 s13, s13, s26
	s_sub_u32 s12, s13, 1280
	s_add_u32 s12, s12, 12288
	s_waitcnt lgkmcnt(0)
	s_cmp_ge_u32 s12, 33280
	s_cbranch_scc1 .Ltrm_done
	s_cmp_ge_u32 s12, 33280
	s_cselect_b32 s41, 1, 0
	s_cselect_b32 s26, 33280, 0
	s_sub_u32 s42, s12, s26
	s_cmp_ge_u32 s42, 12288
	s_cbranch_scc1 .Ltrm_m2
	s_mul_i32 s43, s42, 43691
	s_lshr_b32 s43, s43, 24
	s_mul_i32 s26, s43, 384
	s_sub_u32 s44, s42, s26
	s_mov_b32 s14, s0
	s_mov_b32 s15, s1
	s_mov_b32 s36, 0xc000
	s_mov_b32 s37, 0x6000000
	s_mov_b32 s38, 0x0
	s_mov_b32 s39, 0x3000000
	s_mov_b32 s40, 0x1000
	s_branch .Ltrm_dec_done1

.Ltrm_loop:
	s_add_u32 s12, s12, 768
	s_cmp_lt_u32 s12, 33280
	s_cselect_b32 s24, 1, 0
	s_cbranch_scc0 .Ltrm_nonext8
	s_cmp_ge_u32 s12, 33280
	s_cselect_b32 s41, 1, 0
	s_cselect_b32 s26, 33280, 0
	s_sub_u32 s42, s12, s26
	s_cmp_ge_u32 s42, 12288
	s_cbranch_scc1 .Ltrm_m11
	s_mul_i32 s43, s42, 43691
	s_lshr_b32 s43, s43, 24
	s_mul_i32 s26, s43, 384
	s_sub_u32 s44, s42, s26
	s_mov_b32 s16, s0
	s_mov_b32 s17, s1
	s_mov_b32 s36, 0xc000
	s_mov_b32 s37, 0x6000000
	s_mov_b32 s38, 0x0
	s_mov_b32 s39, 0x3000000
	s_mov_b32 s40, 0x1000
	s_branch .Ltrm_dec_done10

.Ltrm_after9:
	ds_write_b32 v1, v10 offset:0
	ds_write_b32 v1, v11 offset:4
	ds_write_b32 v1, v12 offset:8
	ds_write_b32 v1, v13 offset:12
	ds_write_b32 v1, v14 offset:1056
	ds_write_b32 v1, v15 offset:1060
	ds_write_b32 v1, v16 offset:1064
	ds_write_b32 v1, v17 offset:1068
	ds_write_b32 v1, v18 offset:2112
	ds_write_b32 v1, v19 offset:2116
	ds_write_b32 v1, v20 offset:2120
	ds_write_b32 v1, v21 offset:2124
	ds_write_b32 v1, v22 offset:3168
	ds_write_b32 v1, v23 offset:3172
	ds_write_b32 v1, v24 offset:3176
	ds_write_b32 v1, v25 offset:3180
	ds_write_b32 v1, v26 offset:4224
	ds_write_b32 v1, v27 offset:4228
	ds_write_b32 v1, v28 offset:4232
	ds_write_b32 v1, v29 offset:4236
	ds_write_b32 v1, v30 offset:5280
	ds_write_b32 v1, v31 offset:5284
	ds_write_b32 v1, v32 offset:5288
	ds_write_b32 v1, v33 offset:5292
	ds_write_b32 v1, v34 offset:6336
	ds_write_b32 v1, v35 offset:6340
	ds_write_b32 v1, v36 offset:6344
	ds_write_b32 v1, v37 offset:6348
	ds_write_b32 v1, v38 offset:7392
	ds_write_b32 v1, v39 offset:7396
	ds_write_b32 v1, v40 offset:7400
	ds_write_b32 v1, v41 offset:7404
	v_mad_u32_u24 v9, v5, s22, v6
	s_lshl_b32 s46, s22, 3
	s_waitcnt lgkmcnt(0)
	ds_read_b32 v74, v2 offset:0
	ds_read_b32 v75, v2 offset:132
	ds_read_b32 v76, v2 offset:264
	ds_read_b32 v77, v2 offset:396
	ds_read_b32 v78, v2 offset:528
	ds_read_b32 v79, v2 offset:660
	ds_read_b32 v80, v2 offset:792
	ds_read_b32 v81, v2 offset:924
	ds_read_b32 v82, v2 offset:32
	ds_read_b32 v83, v2 offset:164
	ds_read_b32 v84, v2 offset:296
	ds_read_b32 v85, v2 offset:428
	ds_read_b32 v86, v2 offset:560
	ds_read_b32 v87, v2 offset:692
	ds_read_b32 v88, v2 offset:824
	ds_read_b32 v89, v2 offset:956
	s_waitcnt lgkmcnt(8)
	v_cvt_pk_bf16_f32 v106, v74, v75
	v_cvt_pk_bf16_f32 v107, v76, v77
	v_cvt_pk_bf16_f32 v108, v78, v79
	v_cvt_pk_bf16_f32 v109, v80, v81
	global_store_dwordx4 v9, v[106:109], s[18:19]
	s_add_u32 s18, s18, s46
	s_addc_u32 s19, s19, 0
	ds_read_b32 v90, v2 offset:64
	ds_read_b32 v91, v2 offset:196
	ds_read_b32 v92, v2 offset:328
	ds_read_b32 v93, v2 offset:460
	ds_read_b32 v94, v2 offset:592
	ds_read_b32 v95, v2 offset:724
	ds_read_b32 v96, v2 offset:856
	ds_read_b32 v97, v2 offset:988
	s_waitcnt lgkmcnt(8)
	v_cvt_pk_bf16_f32 v110, v82, v83
	v_cvt_pk_bf16_f32 v111, v84, v85
	v_cvt_pk_bf16_f32 v112, v86, v87
	v_cvt_pk_bf16_f32 v113, v88, v89
	global_store_dwordx4 v9, v[110:113], s[18:19]
	s_add_u32 s18, s18, s46
	s_addc_u32 s19, s19, 0
	ds_read_b32 v98, v2 offset:96
	ds_read_b32 v99, v2 offset:228
	ds_read_b32 v100, v2 offset:360
	ds_read_b32 v101, v2 offset:492
	ds_read_b32 v102, v2 offset:624
	ds_read_b32 v103, v2 offset:756
	ds_read_b32 v104, v2 offset:888
	ds_read_b32 v105, v2 offset:1020
	s_waitcnt lgkmcnt(8)
	v_cvt_pk_bf16_f32 v106, v90, v91
	v_cvt_pk_bf16_f32 v107, v92, v93
	v_cvt_pk_bf16_f32 v108, v94, v95
	v_cvt_pk_bf16_f32 v109, v96, v97
	global_store_dwordx4 v9, v[106:109], s[18:19]
	s_add_u32 s18, s18, s46
	s_addc_u32 s19, s19, 0
	s_waitcnt lgkmcnt(0)
	v_cvt_pk_bf16_f32 v110, v98, v99
	v_cvt_pk_bf16_f32 v111, v100, v101
	v_cvt_pk_bf16_f32 v112, v102, v103
	v_cvt_pk_bf16_f32 v113, v104, v105
	global_store_dwordx4 v9, v[110:113], s[18:19]
	s_cmp_eq_u32 s24, 0
	s_cbranch_scc1 .Ltrm_done
	s_add_u32 s12, s12, 768
	s_cmp_lt_u32 s12, 33280
	s_cselect_b32 s24, 1, 0
	s_cbranch_scc0 .Ltrm_nonext17
	s_cmp_ge_u32 s12, 33280
	s_cselect_b32 s41, 1, 0
	s_cselect_b32 s26, 33280, 0
	s_sub_u32 s42, s12, s26
	s_cmp_ge_u32 s42, 12288
	s_cbranch_scc1 .Ltrm_m20
	s_mul_i32 s43, s42, 43691
	s_lshr_b32 s43, s43, 24
	s_mul_i32 s26, s43, 384
	s_sub_u32 s44, s42, s26
	s_mov_b32 s14, s0
	s_mov_b32 s15, s1
	s_mov_b32 s36, 0xc000
	s_mov_b32 s37, 0x6000000
	s_mov_b32 s38, 0x0
	s_mov_b32 s39, 0x3000000
	s_mov_b32 s40, 0x1000
	s_branch .Ltrm_dec_done19

.Lmix0_done:
	s_barrier
.Lmix0_skip:
	s_add_u32 s24, s90, 0x15918000
	s_addc_u32 s37, s91, 0
	s_add_u32 s38, s90, 0x24918000
	s_mov_b32 s36, s96
	s_addc_u32 s39, s91, 0
	s_cmp_gt_i32 s36, 63
	s_mov_b64 s[0:1], -1
	s_cbranch_scc0 .LBB0_553
	s_sub_i32 s0, s36, 64
	s_lshr_b32 s43, s0, 4
	s_and_b32 s72, s36, 1
	s_bfe_u32 s42, s36, 0x30001
	s_bfe_i32 s2, s36, 0x10000
	s_lshl_b32 s73, s43, 8
	s_lshl_b32 s0, s72, 25
	s_add_u32 s28, s38, s0
	s_addc_u32 s0, s39, 0
	s_and_b32 s29, s0, 0xffff
	s_lshl_b32 s66, s42, 7
	s_and_b32 s25, s37, 0xffff
	s_bitcmp1_b32 s36, 0
	s_cselect_b64 s[0:1], -1, 0
	s_lshl_b32 s3, s72, 11
	v_mov_b32_e32 v6, v154
	s_add_i32 s4, s3, 0x800
	s_and_b32 s33, s2, 0x2a000
	s_or_b32 s40, s4, s33
	v_ashrrev_i32_e32 v57, 7, v6
	s_or_b32 s41, s33, 0x1800
	s_cmp_eq_u32 s72, 0
	v_not_b32_e32 v1, v57
	v_mov_b32_e32 v58, 0x100
	v_lshl_add_u32 v1, v1, 3, v58
	v_lshlrev_b32_e32 v2, 3, v57
	s_cselect_b64 s[6:7], -1, 0
	v_cndmask_b32_e64 v7, v1, v2, s[6:7]
	s_and_b64 s[2:3], s[6:7], exec
	v_and_b32_e32 v12, 0x7f, v6
	v_add_u32_e32 v1, s73, v7
	s_movk_i32 s21, 0x6000
	s_mov_b32 s5, 0xc0000
	s_mov_b32 s2, 0x24000
	s_mov_b32 s3, 0xc000
	s_mov_b32 s31, 0x20000
	s_brev_b32 s26, 48
	v_mul_lo_u32 v1, v1, s21
	v_or_b32_e32 v2, s66, v12
	s_cselect_b32 s44, s5, 0xfff40000
	s_cselect_b32 s45, 0x6000, s2
	s_cselect_b32 s46, s3, 0x1e000
	s_mov_b32 s5, 0x12000
	s_cselect_b32 s49, 0x1e000, s3
	s_mov_b32 s8, s24
	s_mov_b32 s9, s25
	s_mov_b32 s10, s26
	s_mov_b32 s11, s31
	v_lshl_or_b32 v1, v2, 1, v1
	s_cselect_b32 s47, s5, 0x18000
	s_cselect_b32 s48, 0x18000, s5
	s_cselect_b32 s50, s2, 0x6000
	s_cselect_b32 s51, 0x2a000, 0
	s_or_b32 s53, s46, 0x1800
	s_or_b32 s56, s49, 0x1800
	s_or_b32 s59, s4, s45
	s_or_b32 s52, s45, 0x1800
	buffer_load_ushort v2, v1, s[8:11], s41 offen
	buffer_load_ushort v3, v1, s[8:11], s52 offen
	s_or_b32 s54, s47, 0x1800
	s_or_b32 s55, s48, 0x1800
	buffer_load_ushort v4, v1, s[8:11], s53 offen
	buffer_load_ushort v5, v1, s[8:11], s54 offen
	buffer_load_ushort v8, v1, s[8:11], s55 offen
	s_or_b32 s57, s50, 0x1800
	s_or_b32 s58, s51, 0x1800
	buffer_load_ushort v9, v1, s[8:11], s56 offen
	buffer_load_ushort v10, v1, s[8:11], s57 offen
	buffer_load_ushort v11, v1, s[8:11], s58 offen
	buffer_load_ushort v13, v1, s[8:11], s59 offen
	buffer_load_ushort v14, v1, s[8:11], s40 offen
	v_ashrrev_i32_e32 v19, 6, v6
	s_or_b32 s60, s4, s47
	s_or_b32 s61, s4, s49
	v_and_b32_e32 v22, 15, v6
	v_lshlrev_b32_e32 v24, 4, v19
	buffer_load_ushort v15, v1, s[8:11], s60 offen
	s_or_b32 s62, s4, s50
	s_or_b32 s63, s4, s51
	buffer_load_ushort v16, v1, s[8:11], s61 offen
	buffer_load_ushort v42, v1, s[8:11], s50 offen
	buffer_load_ushort v17, v1, s[8:11], s62 offen
	buffer_load_ushort v46, v1, s[8:11], s51 offen
	buffer_load_ushort v18, v1, s[8:11], s63 offen
	s_waitcnt vmcnt(0)
	v_and_or_b32 v59, v24, 48, v22
	s_or_b32 s64, s4, s46
	buffer_load_ushort v45, v1, s[8:11], s33 offen
	buffer_load_ushort v49, v1, s[8:11], s45 offen
	buffer_load_ushort v44, v1, s[8:11], s46 offen
	buffer_load_ushort v24, v1, s[8:11], s64 offen
	s_or_b32 s65, s4, s48
	buffer_load_ushort v48, v1, s[8:11], s47 offen
	buffer_load_ushort v43, v1, s[8:11], s48 offen
	buffer_load_ushort v25, v1, s[8:11], s65 offen
	buffer_load_ushort v47, v1, s[8:11], s49 offen
	s_mov_b32 s74, 0xbfb8aa3b
	s_mov_b32 s75, 0x800000
	v_add_u32_e32 v1, s44, v1
	buffer_load_ushort v26, v1, s[8:11], s33 offen
	buffer_load_ushort v27, v1, s[8:11], s40 offen
	buffer_load_ushort v28, v1, s[8:11], s41 offen
	buffer_load_ushort v29, v1, s[8:11], s45 offen
	buffer_load_ushort v30, v1, s[8:11], s59 offen
	buffer_load_ushort v31, v1, s[8:11], s52 offen
	buffer_load_ushort v32, v1, s[8:11], s46 offen
	buffer_load_ushort v33, v1, s[8:11], s64 offen
	buffer_load_ushort v34, v1, s[8:11], s53 offen
	buffer_load_ushort v35, v1, s[8:11], s47 offen
	buffer_load_ushort v36, v1, s[8:11], s60 offen
	buffer_load_ushort v37, v1, s[8:11], s54 offen
	buffer_load_ushort v38, v1, s[8:11], s48 offen
	buffer_load_ushort v39, v1, s[8:11], s65 offen
	buffer_load_ushort v40, v1, s[8:11], s55 offen
	buffer_load_ushort v41, v1, s[8:11], s49 offen
	buffer_load_ushort v84, v1, s[8:11], s61 offen
	buffer_load_ushort v85, v1, s[8:11], s56 offen
	buffer_load_ushort v86, v1, s[8:11], s50 offen
	buffer_load_ushort v87, v1, s[8:11], s62 offen
	buffer_load_ushort v88, v1, s[8:11], s57 offen
	buffer_load_ushort v89, v1, s[8:11], s51 offen
	buffer_load_ushort v90, v1, s[8:11], s63 offen
	buffer_load_ushort v91, v1, s[8:11], s58 offen
	s_mov_b32 s76, 0x3f317217
	s_mov_b32 s77, 0x7f800000
	v_mov_b32_e32 v61, 0x41b17218
	v_bfe_u32 v23, v6, 4, 2
	v_ashrrev_i32_e32 v20, 8, v6
	v_lshlrev_b32_e32 v68, 3, v23
	v_lshlrev_b32_e32 v69, 7, v20
	v_mul_u32_u24_e32 v70, 0x110, v59
	s_add_i32 s69, 0, 0x1d600
	v_lshlrev_b32_e32 v71, 4, v57
	v_mov_b32_e32 v67, 0
	s_movk_i32 s22, 0x50
	v_add_u32_e32 v73, 0, v71
	s_movk_i32 s2, 0x7f
	s_movk_i32 s3, 0x80
	v_lshlrev_b32_e32 v60, 2, v23
	s_movk_i32 s12, 0x88
	v_lshlrev_b32_e32 v21, 2, v20
	s_lshl_b32 s70, s42, 8
	s_lshl_b32 s71, s44, 1
	s_add_i32 s67, 0, 0x1de00
	v_cmp_gt_i32_e64 s[10:11], 4, v19
	s_add_i32 s68, 0, 0x1cc00
	v_lshlrev_b32_e32 v75, 6, v20
	v_mul_u32_u24_e32 v72, 0x50, v12
	v_mul_lo_u32 v7, v7, s21
	s_mov_b32 s78, 0x5040100
	s_mov_b32 s20, 0
	s_brev_b32 s30, 64
	s_mov_b32 s27, s31
	v_mul_u32_u24_e32 v82, 0x50, v59
	v_lshl_or_b32 v2, v3, 16, v2
	v_lshl_or_b32 v3, v5, 16, v4
	v_lshl_or_b32 v4, v9, 16, v8
	v_lshlrev_b32_e32 v13, 16, v13
	v_lshlrev_b32_e32 v14, 16, v14
	v_mul_f32_e64 v8, |v14|, s74
	v_mul_f32_e64 v9, |v13|, s74
	v_exp_f32_e32 v8, v8
	v_exp_f32_e32 v9, v9
	v_lshl_or_b32 v5, v11, 16, v10
	v_cmp_le_f32_e32 vcc, 0, v14
	v_add_f32_e32 v10, 1.0, v8
	v_add_f32_e32 v11, 1.0, v9
	v_rcp_f32_e32 v10, v10
	v_rcp_f32_e32 v11, v11
	v_lshlrev_b32_e32 v15, 16, v15
	s_waitcnt vmcnt(28)
	v_lshlrev_b32_e32 v24, 16, v24
	v_pk_mul_f32 v[8:9], v[8:9], v[10:11]
	s_nop 0
	v_cndmask_b32_e32 v14, v8, v10, vcc
	v_add_f32_e32 v14, 0, v14
	v_cmp_gt_f32_e64 s[4:5], s75, v14
	s_waitcnt vmcnt(20)
	v_perm_b32 v106, v29, v26, s78
	s_waitcnt vmcnt(14)
	v_perm_b32 v109, v35, v32, s78
	v_cndmask_b32_e64 v50, 0, 32, s[4:5]
	v_ldexp_f32 v14, v14, v50
	v_log_f32_e32 v14, v14
	v_cndmask_b32_e32 v50, v10, v8, vcc
	s_waitcnt vmcnt(8)
	v_perm_b32 v112, v41, v38, s78
	s_waitcnt vmcnt(2)
	v_perm_b32 v115, v89, v86, s78
	v_mul_f32_e32 v1, 0x3f317217, v14
	v_fma_f32 v1, v14, s76, -v1
	v_fmac_f32_e32 v1, 0x3377d1cf, v14
	v_fmac_f32_e32 v1, 0x3f317217, v14
	v_cmp_lt_f32_e64 s[8:9], |v14|, s77
	v_perm_b32 v107, v30, v27, s78
	v_perm_b32 v110, v36, v33, s78
	v_cndmask_b32_e64 v1, v14, v1, s[8:9]
	v_cndmask_b32_e64 v14, 0, v61, s[4:5]
	v_cmp_le_f32_e64 s[4:5], 0, v13
	v_sub_f32_e32 v1, v1, v14
	v_add_f32_e32 v62, 0, v1
	v_cndmask_b32_e64 v13, v9, v11, s[4:5]
	v_add_f32_e32 v13, 0, v13
	v_cmp_gt_f32_e64 s[8:9], s75, v13
	v_cndmask_b32_e64 v1, v11, v9, s[4:5]
	v_mul_f32_e64 v9, |v15|, s74
	v_cndmask_b32_e64 v14, 0, 32, s[8:9]
	v_ldexp_f32 v13, v13, v14
	v_log_f32_e32 v13, v13
	v_exp_f32_e32 v9, v9
	v_perm_b32 v113, v84, v39, s78
	s_waitcnt vmcnt(1)
	v_perm_b32 v116, v90, v87, s78
	v_mul_f32_e32 v8, 0x3f317217, v13
	v_fma_f32 v14, v13, s76, -v8
	v_mul_f32_e64 v8, |v24|, s74
	v_exp_f32_e32 v8, v8
	v_add_f32_e32 v11, 1.0, v9
	v_rcp_f32_e32 v11, v11
	v_fmac_f32_e32 v14, 0x3377d1cf, v13
	v_add_f32_e32 v10, 1.0, v8
	v_rcp_f32_e32 v10, v10
	v_fmac_f32_e32 v14, 0x3f317217, v13
	v_cmp_lt_f32_e64 vcc, |v13|, s77
	v_perm_b32 v108, v31, v28, s78
	v_pk_mul_f32 v[8:9], v[8:9], v[10:11]
	v_cndmask_b32_e32 v13, v13, v14, vcc
	v_cmp_le_f32_e32 vcc, 0, v24
	v_perm_b32 v111, v37, v34, s78
	v_perm_b32 v114, v85, v40, s78
	v_cndmask_b32_e32 v14, v8, v10, vcc
	v_add_f32_e32 v14, 0, v14
	v_cmp_gt_f32_e64 s[4:5], s75, v14
	v_cndmask_b32_e32 v52, v10, v8, vcc
	s_waitcnt vmcnt(0)
	v_perm_b32 v117, v91, v88, s78
	v_cndmask_b32_e64 v24, 0, 32, s[4:5]
	v_ldexp_f32 v14, v14, v24
	v_log_f32_e32 v14, v14
	v_cndmask_b32_e64 v24, 0, v61, s[8:9]
	v_sub_f32_e32 v13, v13, v24
	v_add_f32_e32 v63, v62, v13
	v_mul_f32_e32 v13, 0x3f317217, v14
	v_fma_f32 v13, v14, s76, -v13
	v_fmac_f32_e32 v13, 0x3377d1cf, v14
	v_fmac_f32_e32 v13, 0x3f317217, v14
	v_cmp_lt_f32_e64 s[8:9], |v14|, s77
	v_mov_b32_e32 v24, v67
	v_mov_b32_e32 v26, 0
	v_cndmask_b32_e64 v13, v14, v13, s[8:9]
	v_cndmask_b32_e64 v14, 0, v61, s[4:5]
	v_cmp_le_f32_e64 s[4:5], 0, v15
	v_sub_f32_e32 v13, v13, v14
	v_add_f32_e32 v64, v63, v13
	v_cndmask_b32_e64 v14, v9, v11, s[4:5]
	v_add_f32_e32 v14, 0, v14
	v_cmp_gt_f32_e64 s[8:9], s75, v14
	v_cndmask_b32_e64 v51, v11, v9, s[4:5]
	v_mov_b32_e32 v27, v67
	v_cndmask_b32_e64 v15, 0, 32, s[8:9]
	v_ldexp_f32 v14, v14, v15
	v_log_f32_e32 v14, v14
	v_lshlrev_b32_e32 v15, 16, v16
	v_lshlrev_b32_e32 v16, 16, v25
	v_mul_f32_e64 v9, |v15|, s74
	v_mul_f32_e32 v8, 0x3f317217, v14
	v_fma_f32 v13, v14, s76, -v8
	v_mul_f32_e64 v8, |v16|, s74
	v_exp_f32_e32 v8, v8
	v_exp_f32_e32 v9, v9
	v_fmac_f32_e32 v13, 0x3377d1cf, v14
	v_fmac_f32_e32 v13, 0x3f317217, v14
	v_add_f32_e32 v10, 1.0, v8
	v_add_f32_e32 v11, 1.0, v9
	v_rcp_f32_e32 v10, v10
	v_rcp_f32_e32 v11, v11
	v_cmp_lt_f32_e64 vcc, |v14|, s77
	v_mov_b32_e32 v25, v67
	v_mov_b32_e32 v28, v67
	v_cndmask_b32_e32 v13, v14, v13, vcc
	v_pk_mul_f32 v[8:9], v[8:9], v[10:11]
	v_cmp_le_f32_e32 vcc, 0, v16
	v_mov_b32_e32 v29, v67
	v_mov_b32_e32 v30, 0
	v_cndmask_b32_e32 v14, v8, v10, vcc
	v_add_f32_e32 v14, 0, v14
	v_cmp_gt_f32_e64 s[4:5], s75, v14
	v_cndmask_b32_e32 v54, v10, v8, vcc
	v_mov_b32_e32 v31, v67
	v_cndmask_b32_e64 v16, 0, 32, s[4:5]
	v_ldexp_f32 v14, v14, v16
	v_log_f32_e32 v14, v14
	v_cndmask_b32_e64 v16, 0, v61, s[8:9]
	v_sub_f32_e32 v13, v13, v16
	v_add_f32_e32 v78, v64, v13
	v_mul_f32_e32 v13, 0x3f317217, v14
	v_fma_f32 v13, v14, s76, -v13
	v_fmac_f32_e32 v13, 0x3377d1cf, v14
	v_fmac_f32_e32 v13, 0x3f317217, v14
	v_cmp_lt_f32_e64 s[8:9], |v14|, s77
	v_lshlrev_b32_e32 v16, 16, v17
	v_or_b32_e32 v17, 2, v21
	v_cndmask_b32_e64 v13, v14, v13, s[8:9]
	v_cndmask_b32_e64 v14, 0, v61, s[4:5]
	v_cmp_le_f32_e64 s[4:5], 0, v15
	v_sub_f32_e32 v13, v13, v14
	v_add_f32_e32 v83, v78, v13
	v_cndmask_b32_e64 v14, v9, v11, s[4:5]
	v_add_f32_e32 v14, 0, v14
	v_cmp_gt_f32_e64 s[8:9], s75, v14
	v_cndmask_b32_e64 v53, v11, v9, s[4:5]
	v_mov_b32_e32 v32, v67
	v_cndmask_b32_e64 v15, 0, 32, s[8:9]
	v_ldexp_f32 v14, v14, v15
	v_log_f32_e32 v14, v14
	v_lshlrev_b32_e32 v15, 16, v18
	v_mul_f32_e64 v9, |v15|, s74
	v_exp_f32_e32 v9, v9
	v_mul_f32_e32 v8, 0x3f317217, v14
	v_fma_f32 v13, v14, s76, -v8
	v_mul_f32_e64 v8, |v16|, s74
	v_exp_f32_e32 v8, v8
	v_add_f32_e32 v11, 1.0, v9
	v_rcp_f32_e32 v11, v11
	v_fmac_f32_e32 v13, 0x3377d1cf, v14
	v_add_f32_e32 v10, 1.0, v8
	v_rcp_f32_e32 v10, v10
	v_fmac_f32_e32 v13, 0x3f317217, v14
	v_cmp_lt_f32_e64 vcc, |v14|, s77
	v_lshlrev_b32_e32 v18, 6, v17
	v_pk_mul_f32 v[8:9], v[8:9], v[10:11]
	v_cndmask_b32_e32 v13, v14, v13, vcc
	v_cmp_le_f32_e32 vcc, 0, v16
	v_lshl_or_b32 v17, v17, 4, v22
	v_mul_lo_u32 v17, v17, s22
	v_cndmask_b32_e32 v14, v8, v10, vcc
	v_add_f32_e32 v14, 0, v14
	v_cmp_gt_f32_e64 s[4:5], s75, v14
	v_cndmask_b32_e32 v56, v10, v8, vcc
	v_lshlrev_b32_e32 v10, 2, v12
	v_cndmask_b32_e64 v16, 0, 32, s[4:5]
	v_ldexp_f32 v14, v14, v16
	v_log_f32_e32 v14, v14
	v_cndmask_b32_e64 v16, 0, v61, s[8:9]
	v_sub_f32_e32 v13, v13, v16
	v_add_f32_e32 v99, v83, v13
	v_mul_f32_e32 v13, 0x3f317217, v14
	v_fma_f32 v13, v14, s76, -v13
	v_fmac_f32_e32 v13, 0x3377d1cf, v14
	v_fmac_f32_e32 v13, 0x3f317217, v14
	v_cmp_lt_f32_e64 s[8:9], |v14|, s77
	v_add_u32_e32 v65, s69, v10
	v_lshl_add_u32 v66, v57, 9, v65
	v_cndmask_b32_e64 v13, v14, v13, s[8:9]
	v_cndmask_b32_e64 v14, 0, v61, s[4:5]
	v_cmp_le_f32_e64 s[4:5], 0, v15
	v_sub_f32_e32 v13, v13, v14
	v_add_f32_e32 v100, v99, v13
	v_cndmask_b32_e64 v14, v9, v11, s[4:5]
	v_add_f32_e32 v14, 0, v14
	v_cmp_gt_f32_e64 s[8:9], s75, v14
	v_cndmask_b32_e64 v55, v11, v9, s[4:5]
	v_add_u32_e32 v11, 0, v68
	v_cndmask_b32_e64 v15, 0, 32, s[8:9]
	v_ldexp_f32 v14, v14, v15
	v_log_f32_e32 v14, v14
	v_cndmask_b32_e64 v9, 0, v61, s[8:9]
	v_add3_u32 v11, v11, v69, v70
	v_add_u32_e32 v13, 0xb800, v11
	v_mul_f32_e32 v8, 0x3f317217, v14
	v_fma_f32 v8, v14, s76, -v8
	v_fmac_f32_e32 v8, 0x3377d1cf, v14
	v_fmac_f32_e32 v8, 0x3f317217, v14
	v_cmp_lt_f32_e64 vcc, |v14|, s77
	v_add_u32_e32 v11, 0x4400, v11
	v_add_u32_e32 v11, 0xb800, v11
	v_cndmask_b32_e32 v8, v14, v8, vcc
	v_sub_f32_e32 v8, v8, v9
	v_add_f32_e32 v105, v100, v8
	v_cvt_pk_bf16_f32 v8, v67, v67
	ds_write_b32 v66, v105
	v_mov_b32_e32 v9, v8
	ds_write2_b64 v13, v[8:9], v[8:9] offset0:128 offset1:132
	ds_write2_b64 v13, v[8:9], v[8:9] offset0:136 offset1:140
	ds_write2_b64 v11, v[8:9], v[8:9] offset0:128 offset1:132
	ds_write2_b64 v11, v[8:9], v[8:9] offset0:136 offset1:140
	v_mad_u32_u24 v8, v12, s22, v73
	ds_write_b128 v8, v[2:5] offset:27648
	v_and_b32_e32 v8, 1, v19
	v_cmp_lt_u32_e32 vcc, s2, v6
	v_cmp_eq_u32_e64 s[4:5], 0, v8
	v_cmp_gt_u32_e64 s[8:9], s3, v6
	s_or_b64 s[2:3], vcc, s[4:5]
	v_or_b32_e32 v15, s66, v59
	s_movk_i32 s4, 0x880
	v_lshlrev_b32_e32 v2, 1, v12
	v_lshlrev_b32_e32 v3, 4, v20
	v_or_b32_e32 v11, v60, v71
	v_lshlrev_b32_e32 v77, 2, v15
	v_mul_lo_u32 v15, v57, s4
	v_or_b32_e32 v4, v3, v22
	v_or_b32_e32 v9, v71, v22
	v_lshl_or_b32 v8, v8, 4, v22
	v_add3_u32 v79, 0, v2, v15
	v_mul_u32_u24_e32 v15, 0x88, v59
	v_or_b32_e32 v16, 1, v11
	v_mul_lo_u32 v5, v4, s12
	v_mul_lo_u32 v9, v9, s12
	v_add_lshl_u32 v80, v15, v68, 1
	v_cmp_gt_i32_e64 s[12:13], v8, v11
	v_mul_lo_u32 v15, v11, s22
	v_cmp_gt_i32_e64 s[14:15], v8, v16
	v_or_b32_e32 v16, 2, v11
	v_or_b32_e32 v11, 3, v11
	v_cmp_gt_i32_e64 s[18:19], v8, v11
	v_or_b32_e32 v11, 1, v21
	v_or_b32_e32 v19, 3, v21
	s_mul_i32 s4, s43, 0x600000
	s_or_b32 s5, s71, s70
	s_waitcnt lgkmcnt(0)
	s_barrier
	v_add_u32_e32 v74, s67, v10
	v_mul_u32_u24_e32 v10, 0x88, v8
	v_lshl_add_u32 v12, v8, 1, s68
	v_lshlrev_b32_e32 v13, 4, v23
	v_cmp_gt_i32_e64 s[16:17], v8, v16
	v_or_b32_e32 v8, v75, v22
	v_lshlrev_b32_e32 v16, 6, v11
	v_lshl_or_b32 v11, v11, 4, v22
	v_lshlrev_b32_e32 v20, 6, v19
	v_lshl_or_b32 v19, v19, 4, v22
	s_add_i32 s5, s5, s4
	v_add_u32_e32 v76, 0, v13
	v_add_u32_e32 v14, s67, v13
	v_mul_lo_u32 v4, v4, s22
	v_add_u32_e32 v13, s68, v13
	v_add_lshl_u32 v5, v5, v68, 1
	v_add_lshl_u32 v9, v9, v68, 1
	v_add_lshl_u32 v10, v10, v68, 1
	v_and_b32_e32 v6, 0xffffff00, v6
	v_mul_lo_u32 v8, v8, s22
	v_mul_lo_u32 v11, v11, s22
	v_mul_lo_u32 v19, v19, s22
	v_add_u32_e32 v7, s5, v7
	v_add_u32_e32 v81, 0x4400, v80
	v_or_b32_e32 v84, v7, v2
	v_or_b32_e32 v85, v3, v60
	v_add_u32_e32 v86, 0, v5
	v_add_u32_e32 v87, 0, v9
	v_add_u32_e32 v88, 0, v10
	v_add_u32_e32 v89, v12, v15
	v_add_u32_e32 v90, v14, v6
	v_add_u32_e32 v91, v76, v8
	v_add_u32_e32 v92, v14, v16
	v_add_u32_e32 v93, v76, v11
	v_add_u32_e32 v94, v14, v18
	v_add_u32_e32 v95, v76, v17
	v_add_u32_e32 v96, v14, v20
	v_add_u32_e32 v97, v76, v19
	v_add_u32_e32 v98, v13, v4
	v_mov_b32_e32 v2, 0
	v_mov_b32_e32 v3, v67
	v_mov_b32_e32 v4, v67
	v_mov_b32_e32 v5, v67
	v_mov_b32_e32 v6, 0
	v_mov_b32_e32 v7, v67
	v_mov_b32_e32 v8, v67
	v_mov_b32_e32 v9, v67
	v_mov_b32_e32 v10, 0
	v_mov_b32_e32 v11, v67
	v_mov_b32_e32 v12, v67
	v_mov_b32_e32 v13, v67
	v_mov_b32_e32 v14, 0
	v_mov_b32_e32 v15, v67
	v_mov_b32_e32 v16, v67
	v_mov_b32_e32 v17, v67
	v_mov_b32_e32 v18, 0
	v_mov_b32_e32 v19, v67
	v_mov_b32_e32 v20, v67
	v_mov_b32_e32 v21, v67
	v_mov_b32_e32 v22, 0
	v_mov_b32_e32 v23, v67
	v_mov_b32_e32 v33, v67
	s_branch .LBB0_497

.LBB0_1179:
	s_waitcnt vmcnt(0)
	s_barrier
	s_cmp_lt_u32 s96, 128
	s_cbranch_scc1 .LBB0_1180
	s_load_dwordx2 s[0:1], s[92:93], 0x58
	s_load_dwordx2 s[2:3], s[92:93], 0xb8
	s_load_dwordx2 s[4:5], s[92:93], 0xc0
	s_load_dwordx2 s[6:7], s[92:93], 0xc8
	s_load_dwordx2 s[8:9], s[92:93], 0xd0
	s_load_dwordx2 s[10:11], s[92:93], 0xe8
	v_and_b32_e32 v74, 63, v154
	v_lshrrev_b32_e32 v75, 6, v154
	v_mul_u32_u24_e32 v75, 0x2100, v75
	v_lshrrev_b32_e32 v3, 5, v74
	v_and_b32_e32 v4, 31, v74
	v_lshlrev_b32_e32 v4, 2, v4
	v_lshrrev_b32_e32 v5, 3, v74
	v_and_b32_e32 v6, 7, v74
	v_mul_u32_u24_e32 v2, 264, v6
	v_add_u32_e32 v2, v2, v5
	v_lshl_add_u32 v2, v2, 2, v75
	v_lshlrev_b32_e32 v6, 4, v6
	v_mul_u32_u24_e32 v1, 132, v5
	v_add3_u32 v1, v1, v6, v75
	v_readfirstlane_b32 s13, v154
	s_lshr_b32 s13, s13, 6
	s_lshl_b32 s26, s96, 3
	s_add_u32 s13, s13, s26
	s_sub_u32 s12, s13, 1024
	s_add_u32 s12, s12, 33280
	s_waitcnt lgkmcnt(0)
	s_cmp_ge_u32 s12, 49664
	s_cbranch_scc1 .Ltrs_done
	s_cmp_ge_u32 s12, 33280
	s_cselect_b32 s41, 1, 0
	s_cselect_b32 s26, 33280, 0
	s_sub_u32 s42, s12, s26
	s_cmp_ge_u32 s42, 12288
	s_cbranch_scc1 .Ltrs_m2
	s_mul_i32 s43, s42, 43691
	s_lshr_b32 s43, s43, 24
	s_mul_i32 s26, s43, 384
	s_sub_u32 s44, s42, s26
	s_mov_b32 s14, s0
	s_mov_b32 s15, s1
	s_mov_b32 s36, 0xc000
	s_mov_b32 s37, 0x6000000
	s_mov_b32 s38, 0x0
	s_mov_b32 s39, 0x3000000
	s_mov_b32 s40, 0x1000
	s_branch .Ltrs_dec_done1

.Ltrs_loop:
	s_add_u32 s12, s12, 1024
	s_cmp_lt_u32 s12, 49664
	s_cselect_b32 s24, 1, 0
	s_cbranch_scc0 .Ltrs_nonext8
	s_cmp_ge_u32 s12, 33280
	s_cselect_b32 s41, 1, 0
	s_cselect_b32 s26, 33280, 0
	s_sub_u32 s42, s12, s26
	s_cmp_ge_u32 s42, 12288
	s_cbranch_scc1 .Ltrs_m11
	s_mul_i32 s43, s42, 43691
	s_lshr_b32 s43, s43, 24
	s_mul_i32 s26, s43, 384
	s_sub_u32 s44, s42, s26
	s_mov_b32 s16, s0
	s_mov_b32 s17, s1
	s_mov_b32 s36, 0xc000
	s_mov_b32 s37, 0x6000000
	s_mov_b32 s38, 0x0
	s_mov_b32 s39, 0x3000000
	s_mov_b32 s40, 0x1000
	s_branch .Ltrs_dec_done10

.Ltrs_after9:
	ds_write_b32 v1, v10 offset:0
	ds_write_b32 v1, v11 offset:4
	ds_write_b32 v1, v12 offset:8
	ds_write_b32 v1, v13 offset:12
	ds_write_b32 v1, v14 offset:1056
	ds_write_b32 v1, v15 offset:1060
	ds_write_b32 v1, v16 offset:1064
	ds_write_b32 v1, v17 offset:1068
	ds_write_b32 v1, v18 offset:2112
	ds_write_b32 v1, v19 offset:2116
	ds_write_b32 v1, v20 offset:2120
	ds_write_b32 v1, v21 offset:2124
	ds_write_b32 v1, v22 offset:3168
	ds_write_b32 v1, v23 offset:3172
	ds_write_b32 v1, v24 offset:3176
	ds_write_b32 v1, v25 offset:3180
	ds_write_b32 v1, v26 offset:4224
	ds_write_b32 v1, v27 offset:4228
	ds_write_b32 v1, v28 offset:4232
	ds_write_b32 v1, v29 offset:4236
	ds_write_b32 v1, v30 offset:5280
	ds_write_b32 v1, v31 offset:5284
	ds_write_b32 v1, v32 offset:5288
	ds_write_b32 v1, v33 offset:5292
	ds_write_b32 v1, v34 offset:6336
	ds_write_b32 v1, v35 offset:6340
	ds_write_b32 v1, v36 offset:6344
	ds_write_b32 v1, v37 offset:6348
	ds_write_b32 v1, v38 offset:7392
	ds_write_b32 v1, v39 offset:7396
	ds_write_b32 v1, v40 offset:7400
	ds_write_b32 v1, v41 offset:7404
	v_mad_u32_u24 v9, v5, s22, v6
	s_lshl_b32 s46, s22, 3
	s_waitcnt lgkmcnt(0)
	ds_read_b32 v74, v2 offset:0
	ds_read_b32 v75, v2 offset:132
	ds_read_b32 v76, v2 offset:264
	ds_read_b32 v77, v2 offset:396
	ds_read_b32 v78, v2 offset:528
	ds_read_b32 v79, v2 offset:660
	ds_read_b32 v80, v2 offset:792
	ds_read_b32 v81, v2 offset:924
	ds_read_b32 v82, v2 offset:32
	ds_read_b32 v83, v2 offset:164
	ds_read_b32 v84, v2 offset:296
	ds_read_b32 v85, v2 offset:428
	ds_read_b32 v86, v2 offset:560
	ds_read_b32 v87, v2 offset:692
	ds_read_b32 v88, v2 offset:824
	ds_read_b32 v89, v2 offset:956
	s_waitcnt lgkmcnt(8)
	v_cvt_pk_bf16_f32 v106, v74, v75
	v_cvt_pk_bf16_f32 v107, v76, v77
	v_cvt_pk_bf16_f32 v108, v78, v79
	v_cvt_pk_bf16_f32 v109, v80, v81
	global_store_dwordx4 v9, v[106:109], s[18:19]
	s_add_u32 s18, s18, s46
	s_addc_u32 s19, s19, 0
	ds_read_b32 v90, v2 offset:64
	ds_read_b32 v91, v2 offset:196
	ds_read_b32 v92, v2 offset:328
	ds_read_b32 v93, v2 offset:460
	ds_read_b32 v94, v2 offset:592
	ds_read_b32 v95, v2 offset:724
	ds_read_b32 v96, v2 offset:856
	ds_read_b32 v97, v2 offset:988
	s_waitcnt lgkmcnt(8)
	v_cvt_pk_bf16_f32 v110, v82, v83
	v_cvt_pk_bf16_f32 v111, v84, v85
	v_cvt_pk_bf16_f32 v112, v86, v87
	v_cvt_pk_bf16_f32 v113, v88, v89
	global_store_dwordx4 v9, v[110:113], s[18:19]
	s_add_u32 s18, s18, s46
	s_addc_u32 s19, s19, 0
	ds_read_b32 v98, v2 offset:96
	ds_read_b32 v99, v2 offset:228
	ds_read_b32 v100, v2 offset:360
	ds_read_b32 v101, v2 offset:492
	ds_read_b32 v102, v2 offset:624
	ds_read_b32 v103, v2 offset:756
	ds_read_b32 v104, v2 offset:888
	ds_read_b32 v105, v2 offset:1020
	s_waitcnt lgkmcnt(8)
	v_cvt_pk_bf16_f32 v106, v90, v91
	v_cvt_pk_bf16_f32 v107, v92, v93
	v_cvt_pk_bf16_f32 v108, v94, v95
	v_cvt_pk_bf16_f32 v109, v96, v97
	global_store_dwordx4 v9, v[106:109], s[18:19]
	s_add_u32 s18, s18, s46
	s_addc_u32 s19, s19, 0
	s_waitcnt lgkmcnt(0)
	v_cvt_pk_bf16_f32 v110, v98, v99
	v_cvt_pk_bf16_f32 v111, v100, v101
	v_cvt_pk_bf16_f32 v112, v102, v103
	v_cvt_pk_bf16_f32 v113, v104, v105
	global_store_dwordx4 v9, v[110:113], s[18:19]
	s_cmp_eq_u32 s24, 0
	s_cbranch_scc1 .Ltrs_done
	s_add_u32 s12, s12, 1024
	s_cmp_lt_u32 s12, 49664
	s_cselect_b32 s24, 1, 0
	s_cbranch_scc0 .Ltrs_nonext17
	s_cmp_ge_u32 s12, 33280
	s_cselect_b32 s41, 1, 0
	s_cselect_b32 s26, 33280, 0
	s_sub_u32 s42, s12, s26
	s_cmp_ge_u32 s42, 12288
	s_cbranch_scc1 .Ltrs_m20
	s_mul_i32 s43, s42, 43691
	s_lshr_b32 s43, s43, 24
	s_mul_i32 s26, s43, 384
	s_sub_u32 s44, s42, s26
	s_mov_b32 s14, s0
	s_mov_b32 s15, s1
	s_mov_b32 s36, 0xc000
	s_mov_b32 s37, 0x6000000
	s_mov_b32 s38, 0x0
	s_mov_b32 s39, 0x3000000
	s_mov_b32 s40, 0x1000
	s_branch .Ltrs_dec_done19

.LBB0_1734:
	s_cmp_lt_u32 s96, 160
	s_cbranch_scc1 .Lmix1_skip
	s_load_dwordx2 s[0:1], s[92:93], 0x58
	s_load_dwordx2 s[2:3], s[92:93], 0xb8
	s_load_dwordx2 s[4:5], s[92:93], 0xc0
	s_load_dwordx2 s[6:7], s[92:93], 0xc8
	s_load_dwordx2 s[8:9], s[92:93], 0xd0
	s_load_dwordx2 s[10:11], s[92:93], 0xe8
	v_and_b32_e32 v74, 63, v154
	v_lshrrev_b32_e32 v75, 6, v154
	v_mul_u32_u24_e32 v75, 0x2100, v75
	v_lshrrev_b32_e32 v3, 5, v74
	v_and_b32_e32 v4, 31, v74
	v_lshlrev_b32_e32 v4, 2, v4
	v_lshrrev_b32_e32 v5, 3, v74
	v_and_b32_e32 v6, 7, v74
	v_mul_u32_u24_e32 v2, 264, v6
	v_add_u32_e32 v2, v2, v5
	v_lshl_add_u32 v2, v2, 2, v75
	v_lshlrev_b32_e32 v6, 4, v6
	v_mul_u32_u24_e32 v1, 132, v5
	v_add3_u32 v1, v1, v6, v75
	v_readfirstlane_b32 s13, v154
	s_lshr_b32 s13, s13, 6
	s_lshl_b32 s26, s96, 3
	s_add_u32 s13, s13, s26
	s_sub_u32 s12, s13, 1280
	s_add_u32 s12, s12, 49664
	s_waitcnt lgkmcnt(0)
	s_cmp_ge_u32 s12, 60928
	s_cbranch_scc1 .Ltrn_done
	s_cmp_ge_u32 s12, 33280
	s_cselect_b32 s41, 1, 0
	s_cselect_b32 s26, 33280, 0
	s_sub_u32 s42, s12, s26
	s_cmp_ge_u32 s42, 12288
	s_cbranch_scc1 .Ltrn_m2
	s_mul_i32 s43, s42, 43691
	s_lshr_b32 s43, s43, 24
	s_mul_i32 s26, s43, 384
	s_sub_u32 s44, s42, s26
	s_mov_b32 s14, s0
	s_mov_b32 s15, s1
	s_mov_b32 s36, 0xc000
	s_mov_b32 s37, 0x6000000
	s_mov_b32 s38, 0x0
	s_mov_b32 s39, 0x3000000
	s_mov_b32 s40, 0x1000
	s_branch .Ltrn_dec_done1

.Ltrn_loop:
	s_add_u32 s12, s12, 768
	s_cmp_lt_u32 s12, 60928
	s_cselect_b32 s24, 1, 0
	s_cbranch_scc0 .Ltrn_nonext8
	s_cmp_ge_u32 s12, 33280
	s_cselect_b32 s41, 1, 0
	s_cselect_b32 s26, 33280, 0
	s_sub_u32 s42, s12, s26
	s_cmp_ge_u32 s42, 12288
	s_cbranch_scc1 .Ltrn_m11
	s_mul_i32 s43, s42, 43691
	s_lshr_b32 s43, s43, 24
	s_mul_i32 s26, s43, 384
	s_sub_u32 s44, s42, s26
	s_mov_b32 s16, s0
	s_mov_b32 s17, s1
	s_mov_b32 s36, 0xc000
	s_mov_b32 s37, 0x6000000
	s_mov_b32 s38, 0x0
	s_mov_b32 s39, 0x3000000
	s_mov_b32 s40, 0x1000
	s_branch .Ltrn_dec_done10

.Ltrn_after9:
	ds_write_b32 v1, v10 offset:0
	ds_write_b32 v1, v11 offset:4
	ds_write_b32 v1, v12 offset:8
	ds_write_b32 v1, v13 offset:12
	ds_write_b32 v1, v14 offset:1056
	ds_write_b32 v1, v15 offset:1060
	ds_write_b32 v1, v16 offset:1064
	ds_write_b32 v1, v17 offset:1068
	ds_write_b32 v1, v18 offset:2112
	ds_write_b32 v1, v19 offset:2116
	ds_write_b32 v1, v20 offset:2120
	ds_write_b32 v1, v21 offset:2124
	ds_write_b32 v1, v22 offset:3168
	ds_write_b32 v1, v23 offset:3172
	ds_write_b32 v1, v24 offset:3176
	ds_write_b32 v1, v25 offset:3180
	ds_write_b32 v1, v26 offset:4224
	ds_write_b32 v1, v27 offset:4228
	ds_write_b32 v1, v28 offset:4232
	ds_write_b32 v1, v29 offset:4236
	ds_write_b32 v1, v30 offset:5280
	ds_write_b32 v1, v31 offset:5284
	ds_write_b32 v1, v32 offset:5288
	ds_write_b32 v1, v33 offset:5292
	ds_write_b32 v1, v34 offset:6336
	ds_write_b32 v1, v35 offset:6340
	ds_write_b32 v1, v36 offset:6344
	ds_write_b32 v1, v37 offset:6348
	ds_write_b32 v1, v38 offset:7392
	ds_write_b32 v1, v39 offset:7396
	ds_write_b32 v1, v40 offset:7400
	ds_write_b32 v1, v41 offset:7404
	v_mad_u32_u24 v9, v5, s22, v6
	s_lshl_b32 s46, s22, 3
	s_waitcnt lgkmcnt(0)
	ds_read_b32 v74, v2 offset:0
	ds_read_b32 v75, v2 offset:132
	ds_read_b32 v76, v2 offset:264
	ds_read_b32 v77, v2 offset:396
	ds_read_b32 v78, v2 offset:528
	ds_read_b32 v79, v2 offset:660
	ds_read_b32 v80, v2 offset:792
	ds_read_b32 v81, v2 offset:924
	ds_read_b32 v82, v2 offset:32
	ds_read_b32 v83, v2 offset:164
	ds_read_b32 v84, v2 offset:296
	ds_read_b32 v85, v2 offset:428
	ds_read_b32 v86, v2 offset:560
	ds_read_b32 v87, v2 offset:692
	ds_read_b32 v88, v2 offset:824
	ds_read_b32 v89, v2 offset:956
	s_waitcnt lgkmcnt(8)
	v_cvt_pk_bf16_f32 v106, v74, v75
	v_cvt_pk_bf16_f32 v107, v76, v77
	v_cvt_pk_bf16_f32 v108, v78, v79
	v_cvt_pk_bf16_f32 v109, v80, v81
	global_store_dwordx4 v9, v[106:109], s[18:19]
	s_add_u32 s18, s18, s46
	s_addc_u32 s19, s19, 0
	ds_read_b32 v90, v2 offset:64
	ds_read_b32 v91, v2 offset:196
	ds_read_b32 v92, v2 offset:328
	ds_read_b32 v93, v2 offset:460
	ds_read_b32 v94, v2 offset:592
	ds_read_b32 v95, v2 offset:724
	ds_read_b32 v96, v2 offset:856
	ds_read_b32 v97, v2 offset:988
	s_waitcnt lgkmcnt(8)
	v_cvt_pk_bf16_f32 v110, v82, v83
	v_cvt_pk_bf16_f32 v111, v84, v85
	v_cvt_pk_bf16_f32 v112, v86, v87
	v_cvt_pk_bf16_f32 v113, v88, v89
	global_store_dwordx4 v9, v[110:113], s[18:19]
	s_add_u32 s18, s18, s46
	s_addc_u32 s19, s19, 0
	ds_read_b32 v98, v2 offset:96
	ds_read_b32 v99, v2 offset:228
	ds_read_b32 v100, v2 offset:360
	ds_read_b32 v101, v2 offset:492
	ds_read_b32 v102, v2 offset:624
	ds_read_b32 v103, v2 offset:756
	ds_read_b32 v104, v2 offset:888
	ds_read_b32 v105, v2 offset:1020
	s_waitcnt lgkmcnt(8)
	v_cvt_pk_bf16_f32 v106, v90, v91
	v_cvt_pk_bf16_f32 v107, v92, v93
	v_cvt_pk_bf16_f32 v108, v94, v95
	v_cvt_pk_bf16_f32 v109, v96, v97
	global_store_dwordx4 v9, v[106:109], s[18:19]
	s_add_u32 s18, s18, s46
	s_addc_u32 s19, s19, 0
	s_waitcnt lgkmcnt(0)
	v_cvt_pk_bf16_f32 v110, v98, v99
	v_cvt_pk_bf16_f32 v111, v100, v101
	v_cvt_pk_bf16_f32 v112, v102, v103
	v_cvt_pk_bf16_f32 v113, v104, v105
	global_store_dwordx4 v9, v[110:113], s[18:19]
	s_cmp_eq_u32 s24, 0
	s_cbranch_scc1 .Ltrn_done
	s_add_u32 s12, s12, 768
	s_cmp_lt_u32 s12, 60928
	s_cselect_b32 s24, 1, 0
	s_cbranch_scc0 .Ltrn_nonext17
	s_cmp_ge_u32 s12, 33280
	s_cselect_b32 s41, 1, 0
	s_cselect_b32 s26, 33280, 0
	s_sub_u32 s42, s12, s26
	s_cmp_ge_u32 s42, 12288
	s_cbranch_scc1 .Ltrn_m20
	s_mul_i32 s43, s42, 43691
	s_lshr_b32 s43, s43, 24
	s_mul_i32 s26, s43, 384
	s_sub_u32 s44, s42, s26
	s_mov_b32 s14, s0
	s_mov_b32 s15, s1
	s_mov_b32 s36, 0xc000
	s_mov_b32 s37, 0x6000000
	s_mov_b32 s38, 0x0
	s_mov_b32 s39, 0x3000000
	s_mov_b32 s40, 0x1000
	s_branch .Ltrn_dec_done19

.Lmix1_done:
	s_barrier
.Lmix1_skip:
	s_add_u32 s24, s90, 0x15918000
	s_addc_u32 s39, s91, 0
	s_add_u32 s40, s90, 0x24918000
	s_mov_b32 s38, s96
	s_addc_u32 s41, s91, 0
	s_cmp_gt_i32 s38, 63
	s_mov_b64 s[0:1], -1
	s_cbranch_scc0 .LBB0_1794
	s_sub_i32 s0, s38, 64
	s_lshr_b32 s43, s0, 4
	s_and_b32 s75, s38, 1
	s_bfe_u32 s42, s38, 0x30001
	s_bfe_i32 s4, s38, 0x10000
	s_lshl_b32 s76, s43, 8
	s_lshl_b32 s0, s75, 25
	s_add_u32 s28, s40, s0
	s_waitcnt vmcnt(0)
	v_mov_b32_e32 v6, v154
	s_addc_u32 s0, s41, 0
	s_and_b32 s29, s0, 0xffff
	s_load_dwordx2 s[0:1], s[92:93], 0x60
	s_lshl_b32 s2, s75, 10
	s_lshl_b32 s68, s42, 7
	v_and_b32_e32 v8, 0x7f, v6
	s_or_b32 s69, s68, s2
	v_or_b32_e32 v2, s69, v8
	v_lshlrev_b32_e32 v50, 2, v2
	v_mov_b32_e32 v51, 0
	s_waitcnt lgkmcnt(0)
	v_lshl_add_u64 v[2:3], s[0:1], 0, v[50:51]
	s_movk_i32 s2, 0x2000
	s_and_b32 s25, s39, 0xffff
	v_add_co_u32_e32 v2, vcc, s2, v2
	s_bitcmp1_b32 s38, 0
	s_nop 0
	v_addc_co_u32_e32 v3, vcc, 0, v3, vcc
	s_cselect_b64 s[2:3], -1, 0
	s_lshl_b32 s5, s75, 11
	global_load_dword v4, v50, s[0:1]
	s_add_i32 s13, s5, 0x800
	global_load_dword v2, v[2:3], off
	s_and_b32 s33, s4, 0x2a000
	v_ashrrev_i32_e32 v1, 7, v6
	s_or_b32 s44, s13, s33
	s_or_b32 s45, s33, 0x1800
	s_cmp_eq_u32 s75, 0
	v_not_b32_e32 v3, v1
	v_mov_b32_e32 v50, 0x100
	v_lshl_add_u32 v3, v3, 3, v50
	v_lshlrev_b32_e32 v5, 3, v1
	s_cselect_b64 s[6:7], -1, 0
	v_cndmask_b32_e64 v7, v3, v5, s[6:7]
	s_and_b64 s[4:5], s[6:7], exec
	v_add_u32_e32 v3, s76, v7
	s_movk_i32 s22, 0x6000
	s_mov_b32 s12, 0xc0000
	s_mov_b32 s4, 0x24000
	s_mov_b32 s5, 0xc000
	s_mov_b32 s31, 0x20000
	s_brev_b32 s26, 48
	v_mul_lo_u32 v3, v3, s22
	v_or_b32_e32 v5, s68, v8
	s_cselect_b32 s46, s12, 0xfff40000
	s_cselect_b32 s47, 0x6000, s4
	s_cselect_b32 s48, s5, 0x1e000
	s_mov_b32 s12, 0x12000
	s_cselect_b32 s51, 0x1e000, s5
	s_mov_b32 s8, s24
	s_mov_b32 s9, s25
	s_mov_b32 s10, s26
	s_mov_b32 s11, s31
	v_lshl_or_b32 v9, v5, 1, v3
	s_cselect_b32 s49, s12, 0x18000
	s_cselect_b32 s50, 0x18000, s12
	s_cselect_b32 s52, s4, 0x6000
	s_cselect_b32 s53, 0x2a000, 0
	s_or_b32 s55, s48, 0x1800
	s_or_b32 s58, s51, 0x1800
	s_or_b32 s61, s13, s47
	s_or_b32 s54, s47, 0x1800
	buffer_load_ushort v3, v9, s[8:11], s45 offen
	buffer_load_ushort v5, v9, s[8:11], s54 offen
	s_or_b32 s56, s49, 0x1800
	s_or_b32 s57, s50, 0x1800
	buffer_load_ushort v10, v9, s[8:11], s55 offen
	buffer_load_ushort v11, v9, s[8:11], s56 offen
	buffer_load_ushort v12, v9, s[8:11], s57 offen
	s_or_b32 s59, s52, 0x1800
	s_or_b32 s60, s53, 0x1800
	buffer_load_ushort v13, v9, s[8:11], s58 offen
	buffer_load_ushort v14, v9, s[8:11], s59 offen
	buffer_load_ushort v15, v9, s[8:11], s60 offen
	buffer_load_ushort v16, v9, s[8:11], s61 offen
	buffer_load_ushort v17, v9, s[8:11], s44 offen
	s_or_b32 s62, s13, s49
	s_or_b32 s63, s13, s51
	buffer_load_ushort v18, v9, s[8:11], s62 offen
	s_or_b32 s64, s13, s52
	s_or_b32 s65, s13, s53
	buffer_load_ushort v19, v9, s[8:11], s63 offen
	buffer_load_ushort v42, v9, s[8:11], s52 offen
	buffer_load_ushort v20, v9, s[8:11], s64 offen
	buffer_load_ushort v46, v9, s[8:11], s53 offen
	buffer_load_ushort v21, v9, s[8:11], s65 offen
	s_or_b32 s66, s13, s48
	buffer_load_ushort v45, v9, s[8:11], s33 offen
	buffer_load_ushort v49, v9, s[8:11], s47 offen
	buffer_load_ushort v44, v9, s[8:11], s48 offen
	buffer_load_ushort v27, v9, s[8:11], s66 offen
	s_or_b32 s67, s13, s50
	buffer_load_ushort v48, v9, s[8:11], s49 offen
	buffer_load_ushort v43, v9, s[8:11], s50 offen
	buffer_load_ushort v28, v9, s[8:11], s67 offen
	buffer_load_ushort v47, v9, s[8:11], s51 offen
	v_ashrrev_i32_e32 v22, 6, v6
	v_and_b32_e32 v25, 15, v6
	s_mov_b32 s77, 0xbfb8aa3b
	s_mov_b32 s78, 0x800000
	s_mov_b32 s79, 0x3f317217
	v_add_u32_e32 v9, s46, v9
	s_mov_b32 s80, 0x7f800000
	v_mov_b32_e32 v65, 0x41b17218
	v_bfe_u32 v26, v6, 4, 2
	v_ashrrev_i32_e32 v23, 8, v6
	v_lshlrev_b32_e32 v71, 3, v26
	v_lshlrev_b32_e32 v72, 7, v23
	s_add_i32 s72, 0, 0x1d600
	v_lshlrev_b32_e32 v74, 4, v1
	s_movk_i32 s23, 0x50
	v_add_u32_e32 v76, 0, v74
	s_movk_i32 s12, 0x7f
	v_mul_u32_u24_e32 v75, 0x50, v8
	v_lshlrev_b32_e32 v63, 2, v26
	s_add_i32 s70, 0, 0x1de00
	v_lshlrev_b32_e32 v24, 2, v23
	s_lshl_b32 s73, s42, 8
	s_waitcnt vmcnt(24)
	v_sub_f32_e32 v2, v4, v2
	v_mul_f32_e32 v2, 0x3fb8aa3b, v2
	v_exp_f32_e32 v2, v2
	s_lshl_b32 s74, s46, 1
	s_add_i32 s71, 0, 0x1cc00
	v_lshlrev_b32_e32 v78, 6, v23
	v_add_f32_e32 v2, 1.0, v2
	v_rcp_f32_e32 v64, v2
	v_lshlrev_b32_e32 v2, 4, v22
	v_and_or_b32 v62, v2, 48, v25
	v_mul_u32_u24_e32 v73, 0x110, v62
	v_sub_f32_e32 v52, 1.0, v64
	v_mul_lo_u32 v7, v7, s22
	s_mov_b32 s81, 0x5040100
	s_mov_b32 s34, 0
	s_brev_b32 s30, 64
	s_mov_b32 s27, s31
	v_mul_u32_u24_e32 v85, 0x50, v62
	s_waitcnt vmcnt(22)
	v_lshl_or_b32 v2, v5, 16, v3
	s_waitcnt vmcnt(20)
	v_lshl_or_b32 v3, v11, 16, v10
	s_waitcnt vmcnt(18)
	v_lshl_or_b32 v4, v13, 16, v12
	s_waitcnt vmcnt(16)
	v_lshl_or_b32 v5, v15, 16, v14
	s_waitcnt vmcnt(15)
	v_lshlrev_b32_e32 v14, 16, v16
	s_waitcnt vmcnt(14)
	v_lshlrev_b32_e32 v15, 16, v17
	v_mul_f32_e64 v10, |v15|, s77
	v_mul_f32_e64 v11, |v14|, s77
	v_exp_f32_e32 v10, v10
	v_exp_f32_e32 v11, v11
	v_cmp_le_f32_e32 vcc, 0, v15
	buffer_load_ushort v16, v9, s[8:11], s33 offen
	buffer_load_ushort v17, v9, s[8:11], s44 offen
	buffer_load_ushort v29, v9, s[8:11], s45 offen
	buffer_load_ushort v30, v9, s[8:11], s47 offen
	buffer_load_ushort v31, v9, s[8:11], s61 offen
	buffer_load_ushort v32, v9, s[8:11], s54 offen
	buffer_load_ushort v33, v9, s[8:11], s48 offen
	buffer_load_ushort v34, v9, s[8:11], s66 offen
	v_add_f32_e32 v12, 1.0, v10
	v_add_f32_e32 v13, 1.0, v11
	v_rcp_f32_e32 v12, v12
	v_rcp_f32_e32 v13, v13
	buffer_load_ushort v35, v9, s[8:11], s55 offen
	buffer_load_ushort v36, v9, s[8:11], s49 offen
	buffer_load_ushort v37, v9, s[8:11], s62 offen
	buffer_load_ushort v38, v9, s[8:11], s56 offen
	buffer_load_ushort v39, v9, s[8:11], s50 offen
	buffer_load_ushort v40, v9, s[8:11], s67 offen
	buffer_load_ushort v41, v9, s[8:11], s57 offen
	buffer_load_ushort v87, v9, s[8:11], s51 offen
	buffer_load_ushort v88, v9, s[8:11], s63 offen
	buffer_load_ushort v89, v9, s[8:11], s58 offen
	buffer_load_ushort v90, v9, s[8:11], s52 offen
	buffer_load_ushort v91, v9, s[8:11], s64 offen
	buffer_load_ushort v92, v9, s[8:11], s59 offen
	buffer_load_ushort v93, v9, s[8:11], s53 offen
	buffer_load_ushort v94, v9, s[8:11], s65 offen
	s_nop 0
	buffer_load_ushort v9, v9, s[8:11], s60 offen
	s_waitcnt vmcnt(37)
	v_lshlrev_b32_e32 v18, 16, v18
	v_pk_mul_f32 v[10:11], v[10:11], v[12:13]
	s_waitcnt vmcnt(28)
	v_lshlrev_b32_e32 v27, 16, v27
	v_cndmask_b32_e32 v15, v10, v12, vcc
	v_fma_f32 v15, v52, v15, v64
	v_cmp_gt_f32_e64 s[4:5], s78, v15
	v_lshlrev_b32_e32 v19, 16, v19
	s_waitcnt vmcnt(25)
	v_lshlrev_b32_e32 v28, 16, v28
	v_cndmask_b32_e64 v53, 0, 32, s[4:5]
	v_ldexp_f32 v15, v15, v53
	v_log_f32_e32 v15, v15
	v_cndmask_b32_e64 v54, 0, v65, s[4:5]
	v_cmp_le_f32_e64 s[4:5], 0, v14
	v_cndmask_b32_e32 v14, v12, v10, vcc
	v_mul_f32_e32 v53, 0x3f317217, v15
	v_fma_f32 v53, v15, s79, -v53
	v_fmac_f32_e32 v53, 0x3377d1cf, v15
	v_fmac_f32_e32 v53, 0x3f317217, v15
	v_cmp_lt_f32_e64 s[8:9], |v15|, s80
	v_lshlrev_b32_e32 v21, 16, v21
	v_lshlrev_b32_e32 v20, 16, v20
	v_cndmask_b32_e64 v53, v15, v53, s[8:9]
	v_cndmask_b32_e64 v15, v13, v11, s[4:5]
	v_cndmask_b32_e64 v11, v11, v13, s[4:5]
	v_fma_f32 v11, v52, v11, v64
	v_cmp_gt_f32_e64 s[4:5], s78, v11
	v_cmp_gt_i32_e64 s[10:11], 4, v22
	s_waitcnt vmcnt(20)
	v_perm_b32 v109, v30, v16, s81
	v_cndmask_b32_e64 v13, 0, 32, s[4:5]
	v_ldexp_f32 v11, v11, v13
	v_log_f32_e32 v55, v11
	v_sub_f32_e32 v11, v53, v54
	v_add_f32_e32 v66, 0, v11
	v_mul_f32_e64 v11, |v18|, s77
	v_mul_f32_e32 v10, 0x3f317217, v55
	v_fma_f32 v53, v55, s79, -v10
	v_mul_f32_e64 v10, |v27|, s77
	v_exp_f32_e32 v10, v10
	v_exp_f32_e32 v11, v11
	v_fmac_f32_e32 v53, 0x3377d1cf, v55
	v_fmac_f32_e32 v53, 0x3f317217, v55
	v_add_f32_e32 v12, 1.0, v10
	v_add_f32_e32 v13, 1.0, v11
	v_rcp_f32_e32 v12, v12
	v_rcp_f32_e32 v13, v13
	v_cmp_lt_f32_e64 vcc, |v55|, s80
	v_cndmask_b32_e64 v54, 0, v65, s[4:5]
	s_waitcnt vmcnt(14)
	v_perm_b32 v112, v36, v33, s81
	v_cndmask_b32_e32 v53, v55, v53, vcc
	v_pk_mul_f32 v[10:11], v[10:11], v[12:13]
	v_cmp_le_f32_e32 vcc, 0, v27
	v_sub_f32_e32 v53, v53, v54
	v_add_f32_e32 v67, v66, v53
	v_cndmask_b32_e32 v27, v10, v12, vcc
	v_fma_f32 v27, v52, v27, v64
	v_cmp_gt_f32_e64 s[4:5], s78, v27
	v_mov_b32_e32 v53, v52
	s_waitcnt vmcnt(8)
	v_perm_b32 v115, v87, v39, s81
	v_cndmask_b32_e64 v54, 0, 32, s[4:5]
	v_ldexp_f32 v27, v27, v54
	v_log_f32_e32 v27, v27
	v_pk_mul_f32 v[54:55], v[52:53], v[14:15] op_sel_hi:[0,1]
	s_waitcnt vmcnt(2)
	v_perm_b32 v118, v93, v90, s81
	v_perm_b32 v110, v31, v17, s81
	v_mul_f32_e32 v14, 0x3f317217, v27
	v_fma_f32 v14, v27, s79, -v14
	v_fmac_f32_e32 v14, 0x3377d1cf, v27
	v_fmac_f32_e32 v14, 0x3f317217, v27
	v_cmp_lt_f32_e64 s[8:9], |v27|, s80
	v_perm_b32 v113, v37, v34, s81
	v_perm_b32 v116, v88, v40, s81
	v_cndmask_b32_e64 v14, v27, v14, s[8:9]
	v_cndmask_b32_e64 v27, 0, v65, s[4:5]
	v_cmp_le_f32_e64 s[4:5], 0, v18
	s_waitcnt vmcnt(1)
	v_perm_b32 v119, v94, v91, s81
	v_perm_b32 v111, v32, v29, s81
	v_cndmask_b32_e64 v15, v13, v11, s[4:5]
	v_cndmask_b32_e64 v11, v11, v13, s[4:5]
	v_fma_f32 v11, v52, v11, v64
	v_cmp_gt_f32_e64 s[4:5], s78, v11
	v_perm_b32 v114, v38, v35, s81
	v_perm_b32 v117, v89, v41, s81
	v_cndmask_b32_e64 v13, 0, 32, s[4:5]
	v_ldexp_f32 v11, v11, v13
	v_log_f32_e32 v18, v11
	v_sub_f32_e32 v11, v14, v27
	v_cndmask_b32_e32 v14, v12, v10, vcc
	v_add_f32_e32 v68, v67, v11
	v_mul_f32_e32 v10, 0x3f317217, v18
	v_fma_f32 v27, v18, s79, -v10
	v_mul_f32_e64 v10, |v28|, s77
	v_mul_f32_e64 v11, |v19|, s77
	v_exp_f32_e32 v10, v10
	v_exp_f32_e32 v11, v11
	v_fmac_f32_e32 v27, 0x3377d1cf, v18
	v_fmac_f32_e32 v27, 0x3f317217, v18
	v_add_f32_e32 v12, 1.0, v10
	v_add_f32_e32 v13, 1.0, v11
	v_rcp_f32_e32 v12, v12
	v_rcp_f32_e32 v13, v13
	v_cmp_lt_f32_e64 vcc, |v18|, s80
	s_waitcnt vmcnt(0)
	v_perm_b32 v120, v9, v92, s81
	v_mov_b32_e32 v9, v51
	v_cndmask_b32_e32 v18, v18, v27, vcc
	v_pk_mul_f32 v[10:11], v[10:11], v[12:13]
	v_cmp_le_f32_e32 vcc, 0, v28
	v_cndmask_b32_e64 v27, 0, v65, s[4:5]
	v_sub_f32_e32 v18, v18, v27
	v_cndmask_b32_e32 v28, v10, v12, vcc
	v_fma_f32 v28, v52, v28, v64
	v_cmp_gt_f32_e64 s[4:5], s78, v28
	v_add_f32_e32 v81, v68, v18
	v_mov_b32_e32 v16, v51
	v_cndmask_b32_e64 v56, 0, 32, s[4:5]
	v_ldexp_f32 v28, v28, v56
	v_cndmask_b32_e64 v18, 0, v65, s[4:5]
	v_cmp_le_f32_e64 s[4:5], 0, v19
	v_log_f32_e32 v28, v28
	v_pk_mul_f32 v[56:57], v[52:53], v[14:15] op_sel_hi:[0,1]
	v_cndmask_b32_e64 v15, v13, v11, s[4:5]
	v_cndmask_b32_e64 v11, v11, v13, s[4:5]
	v_fma_f32 v11, v52, v11, v64
	v_cmp_gt_f32_e64 s[4:5], s78, v11
	v_mul_f32_e32 v14, 0x3f317217, v28
	v_fma_f32 v14, v28, s79, -v14
	v_cndmask_b32_e64 v13, 0, 32, s[4:5]
	v_ldexp_f32 v11, v11, v13
	v_log_f32_e32 v19, v11
	v_fmac_f32_e32 v14, 0x3377d1cf, v28
	v_fmac_f32_e32 v14, 0x3f317217, v28
	v_cmp_lt_f32_e64 s[8:9], |v28|, s80
	v_mov_b32_e32 v17, v51
	v_mov_b32_e32 v29, v51
	v_cndmask_b32_e64 v14, v28, v14, s[8:9]
	v_sub_f32_e32 v11, v14, v18
	v_cndmask_b32_e32 v14, v12, v10, vcc
	v_mul_f32_e32 v10, 0x3f317217, v19
	v_add_f32_e32 v86, v81, v11
	v_fma_f32 v18, v19, s79, -v10
	v_mul_f32_e64 v10, |v20|, s77
	v_mul_f32_e64 v11, |v21|, s77
	v_exp_f32_e32 v10, v10
	v_exp_f32_e32 v11, v11
	v_fmac_f32_e32 v18, 0x3377d1cf, v19
	v_fmac_f32_e32 v18, 0x3f317217, v19
	v_add_f32_e32 v12, 1.0, v10
	v_add_f32_e32 v13, 1.0, v11
	v_rcp_f32_e32 v12, v12
	v_rcp_f32_e32 v13, v13
	v_cmp_lt_f32_e64 vcc, |v19|, s80
	v_pk_mul_f32 v[58:59], v[52:53], v[14:15] op_sel_hi:[0,1]
	v_mov_b32_e32 v28, v51
	v_cndmask_b32_e32 v18, v19, v18, vcc
	v_pk_mul_f32 v[10:11], v[10:11], v[12:13]
	v_cmp_le_f32_e32 vcc, 0, v20
	v_cndmask_b32_e64 v19, 0, v65, s[4:5]
	v_sub_f32_e32 v18, v18, v19
	v_cndmask_b32_e32 v20, v10, v12, vcc
	v_fma_f32 v20, v52, v20, v64
	v_cmp_gt_f32_e64 s[4:5], s78, v20
	v_add_f32_e32 v102, v86, v18
	v_mov_b32_e32 v30, 0
	v_cndmask_b32_e64 v27, 0, 32, s[4:5]
	v_ldexp_f32 v20, v20, v27
	v_cndmask_b32_e64 v18, 0, v65, s[4:5]
	v_cmp_le_f32_e64 s[4:5], 0, v21
	v_log_f32_e32 v20, v20
	v_mov_b32_e32 v27, v51
	v_cndmask_b32_e64 v15, v13, v11, s[4:5]
	v_cndmask_b32_e64 v11, v11, v13, s[4:5]
	v_fma_f32 v11, v52, v11, v64
	v_cmp_gt_f32_e64 s[4:5], s78, v11
	v_mul_f32_e32 v14, 0x3f317217, v20
	v_fma_f32 v14, v20, s79, -v14
	v_cndmask_b32_e64 v13, 0, 32, s[4:5]
	v_ldexp_f32 v11, v11, v13
	v_log_f32_e32 v11, v11
	v_fmac_f32_e32 v14, 0x3377d1cf, v20
	v_fmac_f32_e32 v14, 0x3f317217, v20
	v_cmp_lt_f32_e64 s[8:9], |v20|, s80
	v_mov_b32_e32 v31, v51
	v_mov_b32_e32 v32, v51
	v_cndmask_b32_e64 v14, v20, v14, s[8:9]
	v_sub_f32_e32 v13, v14, v18
	v_cndmask_b32_e32 v14, v12, v10, vcc
	v_mul_f32_e32 v10, 0x3f317217, v11
	v_fma_f32 v10, v11, s79, -v10
	v_fmac_f32_e32 v10, 0x3377d1cf, v11
	v_add_f32_e32 v103, v102, v13
	v_fmac_f32_e32 v10, 0x3f317217, v11
	v_cmp_lt_f32_e64 vcc, |v11|, s80
	v_add_u32_e32 v13, 0, v71
	v_lshlrev_b32_e32 v12, 2, v8
	v_cndmask_b32_e32 v10, v11, v10, vcc
	v_cndmask_b32_e64 v11, 0, v65, s[4:5]
	v_add3_u32 v13, v13, v72, v73
	v_sub_f32_e32 v10, v10, v11
	v_pk_mul_f32 v[60:61], v[52:53], v[14:15] op_sel_hi:[0,1]
	v_add_u32_e32 v69, s72, v12
	v_add_u32_e32 v14, 0xb800, v13
	v_add_u32_e32 v13, 0x4400, v13
	v_add_f32_e32 v107, v103, v10
	v_lshl_add_u32 v70, v1, 9, v69
	v_cvt_pk_bf16_f32 v10, v51, v51
	v_add_u32_e32 v13, 0xb800, v13
	v_mov_b32_e32 v11, v10
	ds_write_b32 v70, v107
	ds_write2_b64 v14, v[10:11], v[10:11] offset0:128 offset1:132
	ds_write2_b64 v14, v[10:11], v[10:11] offset0:136 offset1:140
	ds_write2_b64 v13, v[10:11], v[10:11] offset0:128 offset1:132
	ds_write2_b64 v13, v[10:11], v[10:11] offset0:136 offset1:140
	v_mad_u32_u24 v10, v8, s23, v76
	ds_write_b128 v10, v[2:5] offset:27648
	v_lshlrev_b32_e32 v2, 1, v8
	s_movk_i32 s4, 0x80
	v_and_b32_e32 v8, 1, v22
	v_cmp_gt_u32_e64 s[8:9], s4, v6
	v_cmp_lt_u32_e32 vcc, s12, v6
	v_cmp_eq_u32_e64 s[4:5], 0, v8
	s_or_b64 s[20:21], vcc, s[4:5]
	v_or_b32_e32 v18, s68, v62
	s_movk_i32 s4, 0x880
	v_add_u32_e32 v77, s70, v12
	v_lshlrev_b32_e32 v3, 4, v23
	v_or_b32_e32 v12, v63, v74
	v_lshlrev_b32_e32 v80, 2, v18
	v_mul_lo_u32 v18, v1, s4
	v_or_b32_e32 v4, v3, v25
	s_movk_i32 s12, 0x88
	v_or_b32_e32 v10, v74, v25
	v_lshl_or_b32 v8, v8, 4, v25
	v_add3_u32 v82, 0, v2, v18
	v_mul_u32_u24_e32 v18, 0x88, v62
	v_or_b32_e32 v19, 1, v12
	v_mul_lo_u32 v5, v4, s12
	v_mul_lo_u32 v10, v10, s12
	v_add_lshl_u32 v83, v18, v71, 1
	v_cmp_gt_i32_e64 s[12:13], v8, v12
	v_mul_lo_u32 v18, v12, s23
	v_cmp_gt_i32_e64 s[14:15], v8, v19
	v_or_b32_e32 v19, 2, v12
	v_or_b32_e32 v12, 3, v12
	v_cmp_gt_i32_e64 s[18:19], v8, v12
	v_or_b32_e32 v12, 1, v24
	v_or_b32_e32 v20, 2, v24
	v_or_b32_e32 v22, 3, v24
	s_mul_i32 s4, s43, 0x600000
	s_or_b32 s5, s74, s73
	s_waitcnt lgkmcnt(0)
	s_barrier
	v_mul_u32_u24_e32 v11, 0x88, v8
	v_lshl_add_u32 v13, v8, 1, s71
	v_lshlrev_b32_e32 v14, 4, v26
	v_cmp_gt_i32_e64 s[16:17], v8, v19
	v_or_b32_e32 v8, v78, v25
	v_lshlrev_b32_e32 v19, 6, v12
	v_lshl_or_b32 v12, v12, 4, v25
	v_lshlrev_b32_e32 v21, 6, v20
	v_lshl_or_b32 v20, v20, 4, v25
	v_lshlrev_b32_e32 v23, 6, v22
	v_lshl_or_b32 v22, v22, 4, v25
	s_add_i32 s5, s5, s4
	v_add_u32_e32 v79, 0, v14
	v_add_u32_e32 v15, s70, v14
	v_mul_lo_u32 v4, v4, s23
	v_add_u32_e32 v14, s71, v14
	v_add_lshl_u32 v5, v5, v71, 1
	v_add_lshl_u32 v10, v10, v71, 1
	v_add_lshl_u32 v11, v11, v71, 1
	v_and_b32_e32 v6, 0xffffff00, v6
	v_mul_lo_u32 v8, v8, s23
	v_mul_lo_u32 v12, v12, s23
	v_mul_lo_u32 v20, v20, s23
	v_mul_lo_u32 v22, v22, s23
	v_add_u32_e32 v7, s5, v7
	v_add_u32_e32 v84, 0x4400, v83
	v_or_b32_e32 v87, v7, v2
	v_or_b32_e32 v88, v3, v63
	v_add_u32_e32 v89, 0, v5
	v_add_u32_e32 v90, 0, v10
	v_add_u32_e32 v91, 0, v11
	v_add_u32_e32 v92, v13, v18
	v_add_u32_e32 v93, v15, v6
	v_add_u32_e32 v94, v79, v8
	v_add_u32_e32 v95, v15, v19
	v_add_u32_e32 v96, v79, v12
	v_add_u32_e32 v97, v15, v21
	v_add_u32_e32 v98, v79, v20
	v_add_u32_e32 v99, v15, v23
	v_add_u32_e32 v100, v79, v22
	v_add_u32_e32 v101, v14, v4
	v_mov_b32_e32 v2, 0
	v_mov_b32_e32 v3, v51
	v_mov_b32_e32 v4, v51
	v_mov_b32_e32 v5, v51
	v_mov_b32_e32 v6, 0
	v_mov_b32_e32 v7, v51
	v_mov_b32_e32 v8, v51
	v_mov_b32_e32 v10, 0
	v_mov_b32_e32 v11, v51
	v_mov_b32_e32 v12, v51
	v_mov_b32_e32 v13, v51
	v_mov_b32_e32 v14, 0
	v_mov_b32_e32 v15, v51
	v_mov_b32_e32 v18, 0
	v_mov_b32_e32 v19, v51
	v_mov_b32_e32 v20, v51
	v_mov_b32_e32 v21, v51
	v_mov_b32_e32 v22, 0
	v_mov_b32_e32 v23, v51
	v_mov_b32_e32 v24, v51
	v_mov_b32_e32 v25, v51
	v_mov_b32_e32 v26, 0
	v_mov_b32_e32 v33, v51
	s_branch .LBB0_1738
